# attn_post rewritten: 16 loads up front + counted waits instead of 8 serialized load-compute-store rounds; on v091
# speedup vs baseline: 1.0049x; 1.0049x over previous
; __device__ __forceinline__ int tid_opaque() { int t = threadIdx.x; asm volatile("" : "+v"(t)); return t; }
; __device__ __forceinline__ float bf_lo(unsigned w) { return __uint_as_float(w << 16); }
; __device__ __forceinline__ float bf_hi(unsigned w) { return __uint_as_float(w & 0xffff0000u); }
; __device__ __forceinline__ float sumsq8(const f32x4 a, const f32x4 b) { return ((a[0] * a[0] + a[1] * a[1]) + (a[2] * a[2] + a[3] * a[3])) + ((b[0] * b[0] + b[1] * b[1]) + (b[2] * b[2] + b[3] * b[3])); }
; #define GAS __attribute__((address_space(1)))
; __device__ __forceinline__ unsigned pk2(float lo, float hi) { unsigned r; asm("v_cvt_pk_bf16_f32 %0, %1, %2" : "=v"(r) : "v"(lo), "v"(hi)); return r; }
; #define FIN(k) ((const float*)ptab(F.tab, (k)))
; __device__ __forceinline__ void attn_post(Frame& F, int l, int b, int h, int qb, float lam, float oscale) {
;     const int tid_ = tid_opaque(), lane = tid_ & 63, wave_ = __builtin_amdgcn_readfirstlane(tid_ >> 6), rsub = lane >> 4, e8 = (lane & 15) * 8;
;     const float* gs = FIN(I_GSUBLN) + l * 128 + e8; const Who W = who(); const bf16* OV_ = RBUF(RB_OV); bf16* AO_ = RBUF(RB_AO); const f32x4 g0 = *(const f32x4*)gs, g1 = *(const f32x4*)(gs + 4);
;     const size_t rowbase = (size_t)b * SEQ + qb * 256 + wave_ * 32;
; #pragma unroll
;     for (int it = 0; it < 8; ++it) { const size_t row = rowbase + it * 4 + rsub;
;         const v4u a = __builtin_nontemporal_load((const GAS v4u*)(OV_ + row * D + h * 256 + e8)), c = __builtin_nontemporal_load((const GAS v4u*)(OV_ + row * D + h * 256 + 128 + e8));
;         f32x4 d0 = {pg8::bf_lo(a.x) - lam * pg8::bf_lo(c.x), pg8::bf_hi(a.x) - lam * pg8::bf_hi(c.x), pg8::bf_lo(a.y) - lam * pg8::bf_lo(c.y), pg8::bf_hi(a.y) - lam * pg8::bf_hi(c.y)};
;         f32x4 d1 = {pg8::bf_lo(a.z) - lam * pg8::bf_lo(c.z), pg8::bf_hi(a.z) - lam * pg8::bf_hi(c.z), pg8::bf_lo(a.w) - lam * pg8::bf_lo(c.w), pg8::bf_hi(a.w) - lam * pg8::bf_hi(c.w)};
;         float ss = pg8::sumsq8(d0, d1);
;         ss += __shfl_xor(ss, 1); ss += __shfl_xor(ss, 2); ss += __shfl_xor(ss, 4); ss += __shfl_xor(ss, 8);
;         const float rs = __builtin_amdgcn_rsqf(ss * (1.f / 128.f) + 1e-6f) * oscale;
;         d0 = d0 * rs * g0; d1 = d1 * rs * g1;
;         v4u o; o.x = pk2(d0.x, d0.y); o.y = pk2(d0.z, d0.w); o.z = pk2(d1.x, d1.y); o.w = pk2(d1.z, d1.w);
;         *(GAS v4u*)(AO_ + row * D + h * 128 + e8) = o; }
.LBB0_362:
	v_lshlrev_b32_e32 v0, 3, v2
	s_add_u32 s16, s20, s4
	v_and_b32_e32 v12, 0x78, v0
	s_addc_u32 s17, s19, s5
	v_lshlrev_b32_e32 v4, 2, v12
	v_lshrrev_b32_e32 v8, 4, v2
	global_load_dwordx4 v[0:3], v4, s[16:17] offset:16
	s_nop 0
	global_load_dwordx4 v[4:7], v4, s[16:17]
	s_ashr_i32 s16, s18, 1
	s_or_b32 s19, s10, s77
	s_andn2_b32 s16, s16, 31
	s_ashr_i32 s17, s16, 31
	v_and_or_b32 v8, v8, 3, s19
	v_mov_b32_e32 v9, s11
	v_lshl_add_u64 v[10:11], v[8:9], 0, s[16:17]
	s_add_u32 s0, s0, s71
	s_addc_u32 s1, s1, 0
	v_lshlrev_b64 v[10:11], 11, v[10:11]
	v_lshlrev_b32_e32 v194, 1, v12
	v_lshl_add_u64 v[12:13], s[0:1], 0, v[10:11]
	v_lshl_add_u64 v[16:17], v[12:13], 0, v[194:195]
	s_mov_b32 s98, 0x2000
	s_mov_b32 s99, 0
	s_add_u32 s14, s14, s76
	s_addc_u32 s15, s15, 0
	v_lshl_add_u64 v[8:9], s[14:15], 0, v[194:195]
	s_and_b64 vcc, exec, s[12:13]
	v_mov_b64_e32 v[100:101], v[16:17]
	v_lshl_add_u64 v[102:103], v[8:9], 0, v[10:11]
	global_load_dwordx4 v[32:35], v[100:101], off nt
	global_load_dwordx4 v[36:39], v[100:101], off offset:256 nt
	v_lshl_add_u64 v[100:101], v[100:101], 0, s[98:99]
	global_load_dwordx4 v[40:43], v[100:101], off nt
	global_load_dwordx4 v[44:47], v[100:101], off offset:256 nt
	v_lshl_add_u64 v[100:101], v[100:101], 0, s[98:99]
	global_load_dwordx4 v[48:51], v[100:101], off nt
	global_load_dwordx4 v[52:55], v[100:101], off offset:256 nt
	v_lshl_add_u64 v[100:101], v[100:101], 0, s[98:99]
	global_load_dwordx4 v[56:59], v[100:101], off nt
	global_load_dwordx4 v[60:63], v[100:101], off offset:256 nt
	v_lshl_add_u64 v[100:101], v[100:101], 0, s[98:99]
	global_load_dwordx4 v[64:67], v[100:101], off nt
	global_load_dwordx4 v[68:71], v[100:101], off offset:256 nt
	v_lshl_add_u64 v[100:101], v[100:101], 0, s[98:99]
	global_load_dwordx4 v[72:75], v[100:101], off nt
	global_load_dwordx4 v[76:79], v[100:101], off offset:256 nt
	v_lshl_add_u64 v[100:101], v[100:101], 0, s[98:99]
	global_load_dwordx4 v[80:83], v[100:101], off nt
	global_load_dwordx4 v[84:87], v[100:101], off offset:256 nt
	v_lshl_add_u64 v[100:101], v[100:101], 0, s[98:99]
	global_load_dwordx4 v[88:91], v[100:101], off nt
	global_load_dwordx4 v[92:95], v[100:101], off offset:256 nt
	s_waitcnt vmcnt(14)
	v_lshlrev_b32_e32 v112, 16, v32
	v_and_b32_e32 v113, 0xffff0000, v32
	v_lshlrev_b32_e32 v114, 16, v36
	v_and_b32_e32 v115, 0xffff0000, v36
	v_fma_f32 v104, -v188, v114, v112
	v_fma_f32 v105, -v188, v115, v113
	v_lshlrev_b32_e32 v112, 16, v33
	v_and_b32_e32 v113, 0xffff0000, v33
	v_lshlrev_b32_e32 v114, 16, v37
	v_and_b32_e32 v115, 0xffff0000, v37
	v_fma_f32 v106, -v188, v114, v112
	v_fma_f32 v107, -v188, v115, v113
	v_lshlrev_b32_e32 v112, 16, v34
	v_and_b32_e32 v113, 0xffff0000, v34
	v_lshlrev_b32_e32 v114, 16, v38
	v_and_b32_e32 v115, 0xffff0000, v38
	v_fma_f32 v108, -v188, v114, v112
	v_fma_f32 v109, -v188, v115, v113
	v_lshlrev_b32_e32 v112, 16, v35
	v_and_b32_e32 v113, 0xffff0000, v35
	v_lshlrev_b32_e32 v114, 16, v39
	v_and_b32_e32 v115, 0xffff0000, v39
	v_fma_f32 v110, -v188, v114, v112
	v_fma_f32 v111, -v188, v115, v113
	v_mul_f32_e32 v116, v104, v104
	v_mul_f32_e32 v117, v105, v105
	v_fmac_f32_e32 v116, v106, v106
	v_fmac_f32_e32 v117, v107, v107
	v_fmac_f32_e32 v116, v108, v108
	v_fmac_f32_e32 v117, v109, v109
	v_fmac_f32_e32 v116, v110, v110
	v_fmac_f32_e32 v117, v111, v111
	v_add_f32_e32 v116, v116, v117
	ds_bpermute_b32 v118, v207, v116
	s_waitcnt lgkmcnt(0)
	v_add_f32_e32 v116, v116, v118
	ds_bpermute_b32 v118, v208, v116
	s_waitcnt lgkmcnt(0)
	v_add_f32_e32 v116, v116, v118
	ds_bpermute_b32 v118, v209, v116
	s_waitcnt lgkmcnt(0)
	v_add_f32_e32 v116, v116, v118
	ds_bpermute_b32 v118, v210, v116
	s_waitcnt lgkmcnt(0)
	v_add_f32_e32 v116, v116, v118
	v_fmamk_f32 v116, v116, 0x3c000000, v193
	v_rsq_f32_e32 v120, v116
	s_nop 0
	v_mul_f32_e32 v120, v211, v120
	v_mul_f32_e32 v104, v104, v120
	v_mul_f32_e32 v105, v105, v120
	v_mul_f32_e32 v106, v106, v120
	v_mul_f32_e32 v107, v107, v120
	v_mul_f32_e32 v108, v108, v120
	v_mul_f32_e32 v109, v109, v120
	v_mul_f32_e32 v110, v110, v120
	v_mul_f32_e32 v111, v111, v120
	v_mul_f32_e32 v104, v4, v104
	v_mul_f32_e32 v105, v5, v105
	v_mul_f32_e32 v106, v6, v106
	v_mul_f32_e32 v107, v7, v107
	v_mul_f32_e32 v108, v0, v108
	v_mul_f32_e32 v109, v1, v109
	v_mul_f32_e32 v110, v2, v110
	v_mul_f32_e32 v111, v3, v111
	v_cvt_pk_bf16_f32 v124, v104, v105
	v_cvt_pk_bf16_f32 v125, v106, v107
	v_cvt_pk_bf16_f32 v126, v108, v109
	v_cvt_pk_bf16_f32 v127, v110, v111
	global_store_dwordx4 v[102:103], v[124:127], off
	v_lshl_add_u64 v[102:103], v[102:103], 0, s[98:99]
	s_waitcnt vmcnt(13)
	v_lshlrev_b32_e32 v112, 16, v40
	v_and_b32_e32 v113, 0xffff0000, v40
	v_lshlrev_b32_e32 v114, 16, v44
	v_and_b32_e32 v115, 0xffff0000, v44
	v_fma_f32 v104, -v188, v114, v112
	v_fma_f32 v105, -v188, v115, v113
	v_lshlrev_b32_e32 v112, 16, v41
	v_and_b32_e32 v113, 0xffff0000, v41
	v_lshlrev_b32_e32 v114, 16, v45
	v_and_b32_e32 v115, 0xffff0000, v45
	v_fma_f32 v106, -v188, v114, v112
	v_fma_f32 v107, -v188, v115, v113
	v_lshlrev_b32_e32 v112, 16, v42
	v_and_b32_e32 v113, 0xffff0000, v42
	v_lshlrev_b32_e32 v114, 16, v46
	v_and_b32_e32 v115, 0xffff0000, v46
	v_fma_f32 v108, -v188, v114, v112
	v_fma_f32 v109, -v188, v115, v113
	v_lshlrev_b32_e32 v112, 16, v43
	v_and_b32_e32 v113, 0xffff0000, v43
	v_lshlrev_b32_e32 v114, 16, v47
	v_and_b32_e32 v115, 0xffff0000, v47
	v_fma_f32 v110, -v188, v114, v112
	v_fma_f32 v111, -v188, v115, v113
	v_mul_f32_e32 v116, v104, v104
	v_mul_f32_e32 v117, v105, v105
	v_fmac_f32_e32 v116, v106, v106
	v_fmac_f32_e32 v117, v107, v107
	v_fmac_f32_e32 v116, v108, v108
	v_fmac_f32_e32 v117, v109, v109
	v_fmac_f32_e32 v116, v110, v110
	v_fmac_f32_e32 v117, v111, v111
	v_add_f32_e32 v116, v116, v117
	ds_bpermute_b32 v118, v207, v116
	s_waitcnt lgkmcnt(0)
; __device__ __forceinline__ float bf_lo(unsigned w) { return __uint_as_float(w << 16); }
; __device__ __forceinline__ float bf_hi(unsigned w) { return __uint_as_float(w & 0xffff0000u); }
; __device__ __forceinline__ float sumsq8(const f32x4 a, const f32x4 b) { return ((a[0] * a[0] + a[1] * a[1]) + (a[2] * a[2] + a[3] * a[3])) + ((b[0] * b[0] + b[1] * b[1]) + (b[2] * b[2] + b[3] * b[3])); }
; #define GAS __attribute__((address_space(1)))
; __device__ __forceinline__ unsigned pk2(float lo, float hi) { unsigned r; asm("v_cvt_pk_bf16_f32 %0, %1, %2" : "=v"(r) : "v"(lo), "v"(hi)); return r; }
; __device__ __forceinline__ void attn_post(Frame& F, int l, int b, int h, int qb, float lam, float oscale) {
;     ...
;     for (int it = 0; it < 8; ++it) { const size_t row = rowbase + it * 4 + rsub;
;         const v4u a = __builtin_nontemporal_load((const GAS v4u*)(OV_ + row * D + h * 256 + e8)), c = __builtin_nontemporal_load((const GAS v4u*)(OV_ + row * D + h * 256 + 128 + e8));
;         f32x4 d0 = {pg8::bf_lo(a.x) - lam * pg8::bf_lo(c.x), pg8::bf_hi(a.x) - lam * pg8::bf_hi(c.x), pg8::bf_lo(a.y) - lam * pg8::bf_lo(c.y), pg8::bf_hi(a.y) - lam * pg8::bf_hi(c.y)};
;         f32x4 d1 = {pg8::bf_lo(a.z) - lam * pg8::bf_lo(c.z), pg8::bf_hi(a.z) - lam * pg8::bf_hi(c.z), pg8::bf_lo(a.w) - lam * pg8::bf_lo(c.w), pg8::bf_hi(a.w) - lam * pg8::bf_hi(c.w)};
;         float ss = pg8::sumsq8(d0, d1);
;         ss += __shfl_xor(ss, 1); ss += __shfl_xor(ss, 2); ss += __shfl_xor(ss, 4); ss += __shfl_xor(ss, 8);
;         const float rs = __builtin_amdgcn_rsqf(ss * (1.f / 128.f) + 1e-6f) * oscale;
;         d0 = d0 * rs * g0; d1 = d1 * rs * g1;
;         v4u o; o.x = pk2(d0.x, d0.y); o.y = pk2(d0.z, d0.w); o.z = pk2(d1.x, d1.y); o.w = pk2(d1.z, d1.w);
;         *(GAS v4u*)(AO_ + row * D + h * 128 + e8) = o; }
	v_add_f32_e32 v116, v116, v118
	ds_bpermute_b32 v118, v208, v116
	s_waitcnt lgkmcnt(0)
	v_add_f32_e32 v116, v116, v118
	ds_bpermute_b32 v118, v209, v116
	s_waitcnt lgkmcnt(0)
	v_add_f32_e32 v116, v116, v118
	ds_bpermute_b32 v118, v210, v116
	s_waitcnt lgkmcnt(0)
	v_add_f32_e32 v116, v116, v118
	v_fmamk_f32 v116, v116, 0x3c000000, v193
	v_rsq_f32_e32 v120, v116
	s_nop 0
	v_mul_f32_e32 v120, v211, v120
	v_mul_f32_e32 v104, v104, v120
	v_mul_f32_e32 v105, v105, v120
	v_mul_f32_e32 v106, v106, v120
	v_mul_f32_e32 v107, v107, v120
	v_mul_f32_e32 v108, v108, v120
	v_mul_f32_e32 v109, v109, v120
	v_mul_f32_e32 v110, v110, v120
	v_mul_f32_e32 v111, v111, v120
	v_mul_f32_e32 v104, v4, v104
	v_mul_f32_e32 v105, v5, v105
	v_mul_f32_e32 v106, v6, v106
	v_mul_f32_e32 v107, v7, v107
	v_mul_f32_e32 v108, v0, v108
	v_mul_f32_e32 v109, v1, v109
	v_mul_f32_e32 v110, v2, v110
	v_mul_f32_e32 v111, v3, v111
	v_cvt_pk_bf16_f32 v124, v104, v105
	v_cvt_pk_bf16_f32 v125, v106, v107
	v_cvt_pk_bf16_f32 v126, v108, v109
	v_cvt_pk_bf16_f32 v127, v110, v111
	global_store_dwordx4 v[102:103], v[124:127], off
	v_lshl_add_u64 v[102:103], v[102:103], 0, s[98:99]
	s_waitcnt vmcnt(12)
	v_lshlrev_b32_e32 v112, 16, v48
	v_and_b32_e32 v113, 0xffff0000, v48
	v_lshlrev_b32_e32 v114, 16, v52
	v_and_b32_e32 v115, 0xffff0000, v52
	v_fma_f32 v104, -v188, v114, v112
	v_fma_f32 v105, -v188, v115, v113
	v_lshlrev_b32_e32 v112, 16, v49
	v_and_b32_e32 v113, 0xffff0000, v49
	v_lshlrev_b32_e32 v114, 16, v53
	v_and_b32_e32 v115, 0xffff0000, v53
	v_fma_f32 v106, -v188, v114, v112
	v_fma_f32 v107, -v188, v115, v113
	v_lshlrev_b32_e32 v112, 16, v50
	v_and_b32_e32 v113, 0xffff0000, v50
	v_lshlrev_b32_e32 v114, 16, v54
	v_and_b32_e32 v115, 0xffff0000, v54
	v_fma_f32 v108, -v188, v114, v112
	v_fma_f32 v109, -v188, v115, v113
	v_lshlrev_b32_e32 v112, 16, v51
	v_and_b32_e32 v113, 0xffff0000, v51
	v_lshlrev_b32_e32 v114, 16, v55
	v_and_b32_e32 v115, 0xffff0000, v55
	v_fma_f32 v110, -v188, v114, v112
	v_fma_f32 v111, -v188, v115, v113
	v_mul_f32_e32 v116, v104, v104
	v_mul_f32_e32 v117, v105, v105
	v_fmac_f32_e32 v116, v106, v106
	v_fmac_f32_e32 v117, v107, v107
	v_fmac_f32_e32 v116, v108, v108
	v_fmac_f32_e32 v117, v109, v109
	v_fmac_f32_e32 v116, v110, v110
	v_fmac_f32_e32 v117, v111, v111
	v_add_f32_e32 v116, v116, v117
	ds_bpermute_b32 v118, v207, v116
	s_waitcnt lgkmcnt(0)
	v_add_f32_e32 v116, v116, v118
	ds_bpermute_b32 v118, v208, v116
	s_waitcnt lgkmcnt(0)
	v_add_f32_e32 v116, v116, v118
	ds_bpermute_b32 v118, v209, v116
	s_waitcnt lgkmcnt(0)
	v_add_f32_e32 v116, v116, v118
	ds_bpermute_b32 v118, v210, v116
	s_waitcnt lgkmcnt(0)
	v_add_f32_e32 v116, v116, v118
	v_fmamk_f32 v116, v116, 0x3c000000, v193
	v_rsq_f32_e32 v120, v116
	s_nop 0
	v_mul_f32_e32 v120, v211, v120
	v_mul_f32_e32 v104, v104, v120
	v_mul_f32_e32 v105, v105, v120
	v_mul_f32_e32 v106, v106, v120
	v_mul_f32_e32 v107, v107, v120
	v_mul_f32_e32 v108, v108, v120
	v_mul_f32_e32 v109, v109, v120
	v_mul_f32_e32 v110, v110, v120
	v_mul_f32_e32 v111, v111, v120
	v_mul_f32_e32 v104, v4, v104
	v_mul_f32_e32 v105, v5, v105
	v_mul_f32_e32 v106, v6, v106
	v_mul_f32_e32 v107, v7, v107
	v_mul_f32_e32 v108, v0, v108
	v_mul_f32_e32 v109, v1, v109
	v_mul_f32_e32 v110, v2, v110
	v_mul_f32_e32 v111, v3, v111
	v_cvt_pk_bf16_f32 v124, v104, v105
	v_cvt_pk_bf16_f32 v125, v106, v107
	v_cvt_pk_bf16_f32 v126, v108, v109
	v_cvt_pk_bf16_f32 v127, v110, v111
	global_store_dwordx4 v[102:103], v[124:127], off
	v_lshl_add_u64 v[102:103], v[102:103], 0, s[98:99]
	s_waitcnt vmcnt(11)
	v_lshlrev_b32_e32 v112, 16, v56
	v_and_b32_e32 v113, 0xffff0000, v56
	v_lshlrev_b32_e32 v114, 16, v60
	v_and_b32_e32 v115, 0xffff0000, v60
	v_fma_f32 v104, -v188, v114, v112
	v_fma_f32 v105, -v188, v115, v113
	v_lshlrev_b32_e32 v112, 16, v57
	v_and_b32_e32 v113, 0xffff0000, v57
	v_lshlrev_b32_e32 v114, 16, v61
	v_and_b32_e32 v115, 0xffff0000, v61
	v_fma_f32 v106, -v188, v114, v112
	v_fma_f32 v107, -v188, v115, v113
	v_lshlrev_b32_e32 v112, 16, v58
	v_and_b32_e32 v113, 0xffff0000, v58
	v_lshlrev_b32_e32 v114, 16, v62
	v_and_b32_e32 v115, 0xffff0000, v62
	v_fma_f32 v108, -v188, v114, v112
	v_fma_f32 v109, -v188, v115, v113
	v_lshlrev_b32_e32 v112, 16, v59
	v_and_b32_e32 v113, 0xffff0000, v59
	v_lshlrev_b32_e32 v114, 16, v63
	v_and_b32_e32 v115, 0xffff0000, v63
	v_fma_f32 v110, -v188, v114, v112
	v_fma_f32 v111, -v188, v115, v113
	v_mul_f32_e32 v116, v104, v104
	v_mul_f32_e32 v117, v105, v105
	v_fmac_f32_e32 v116, v106, v106
	v_fmac_f32_e32 v117, v107, v107
	v_fmac_f32_e32 v116, v108, v108
	v_fmac_f32_e32 v117, v109, v109
	v_fmac_f32_e32 v116, v110, v110
	v_fmac_f32_e32 v117, v111, v111
	v_add_f32_e32 v116, v116, v117
	ds_bpermute_b32 v118, v207, v116
	s_waitcnt lgkmcnt(0)
	v_add_f32_e32 v116, v116, v118
	ds_bpermute_b32 v118, v208, v116
	s_waitcnt lgkmcnt(0)
	v_add_f32_e32 v116, v116, v118
	ds_bpermute_b32 v118, v209, v116
	s_waitcnt lgkmcnt(0)
	v_add_f32_e32 v116, v116, v118
	ds_bpermute_b32 v118, v210, v116
	s_waitcnt lgkmcnt(0)
	v_add_f32_e32 v116, v116, v118
	v_fmamk_f32 v116, v116, 0x3c000000, v193
	v_rsq_f32_e32 v120, v116
	s_nop 0
	v_mul_f32_e32 v120, v211, v120
	v_mul_f32_e32 v104, v104, v120
	v_mul_f32_e32 v105, v105, v120
	v_mul_f32_e32 v106, v106, v120
	v_mul_f32_e32 v107, v107, v120
	v_mul_f32_e32 v108, v108, v120
	v_mul_f32_e32 v109, v109, v120
	v_mul_f32_e32 v110, v110, v120
	v_mul_f32_e32 v111, v111, v120
	v_mul_f32_e32 v104, v4, v104
	v_mul_f32_e32 v105, v5, v105
	v_mul_f32_e32 v106, v6, v106
	v_mul_f32_e32 v107, v7, v107
	v_mul_f32_e32 v108, v0, v108
	v_mul_f32_e32 v109, v1, v109
	v_mul_f32_e32 v110, v2, v110
	v_mul_f32_e32 v111, v3, v111
	v_cvt_pk_bf16_f32 v124, v104, v105
	v_cvt_pk_bf16_f32 v125, v106, v107
	v_cvt_pk_bf16_f32 v126, v108, v109
	v_cvt_pk_bf16_f32 v127, v110, v111
	global_store_dwordx4 v[102:103], v[124:127], off
	v_lshl_add_u64 v[102:103], v[102:103], 0, s[98:99]
	s_waitcnt vmcnt(10)
; __device__ __forceinline__ float bf_lo(unsigned w) { return __uint_as_float(w << 16); }
; __device__ __forceinline__ float bf_hi(unsigned w) { return __uint_as_float(w & 0xffff0000u); }
; __device__ __forceinline__ float sumsq8(const f32x4 a, const f32x4 b) { return ((a[0] * a[0] + a[1] * a[1]) + (a[2] * a[2] + a[3] * a[3])) + ((b[0] * b[0] + b[1] * b[1]) + (b[2] * b[2] + b[3] * b[3])); }
; #define GAS __attribute__((address_space(1)))
; __device__ __forceinline__ unsigned pk2(float lo, float hi) { unsigned r; asm("v_cvt_pk_bf16_f32 %0, %1, %2" : "=v"(r) : "v"(lo), "v"(hi)); return r; }
; __device__ __forceinline__ void attn_post(Frame& F, int l, int b, int h, int qb, float lam, float oscale) {
;     ...
;     for (int it = 0; it < 8; ++it) { const size_t row = rowbase + it * 4 + rsub;
;         const v4u a = __builtin_nontemporal_load((const GAS v4u*)(OV_ + row * D + h * 256 + e8)), c = __builtin_nontemporal_load((const GAS v4u*)(OV_ + row * D + h * 256 + 128 + e8));
;         f32x4 d0 = {pg8::bf_lo(a.x) - lam * pg8::bf_lo(c.x), pg8::bf_hi(a.x) - lam * pg8::bf_hi(c.x), pg8::bf_lo(a.y) - lam * pg8::bf_lo(c.y), pg8::bf_hi(a.y) - lam * pg8::bf_hi(c.y)};
;         f32x4 d1 = {pg8::bf_lo(a.z) - lam * pg8::bf_lo(c.z), pg8::bf_hi(a.z) - lam * pg8::bf_hi(c.z), pg8::bf_lo(a.w) - lam * pg8::bf_lo(c.w), pg8::bf_hi(a.w) - lam * pg8::bf_hi(c.w)};
;         float ss = pg8::sumsq8(d0, d1);
;         ss += __shfl_xor(ss, 1); ss += __shfl_xor(ss, 2); ss += __shfl_xor(ss, 4); ss += __shfl_xor(ss, 8);
;         const float rs = __builtin_amdgcn_rsqf(ss * (1.f / 128.f) + 1e-6f) * oscale;
;         d0 = d0 * rs * g0; d1 = d1 * rs * g1;
;         v4u o; o.x = pk2(d0.x, d0.y); o.y = pk2(d0.z, d0.w); o.z = pk2(d1.x, d1.y); o.w = pk2(d1.z, d1.w);
;         *(GAS v4u*)(AO_ + row * D + h * 128 + e8) = o; }
	v_lshlrev_b32_e32 v112, 16, v64
	v_and_b32_e32 v113, 0xffff0000, v64
	v_lshlrev_b32_e32 v114, 16, v68
	v_and_b32_e32 v115, 0xffff0000, v68
	v_fma_f32 v104, -v188, v114, v112
	v_fma_f32 v105, -v188, v115, v113
	v_lshlrev_b32_e32 v112, 16, v65
	v_and_b32_e32 v113, 0xffff0000, v65
	v_lshlrev_b32_e32 v114, 16, v69
	v_and_b32_e32 v115, 0xffff0000, v69
	v_fma_f32 v106, -v188, v114, v112
	v_fma_f32 v107, -v188, v115, v113
	v_lshlrev_b32_e32 v112, 16, v66
	v_and_b32_e32 v113, 0xffff0000, v66
	v_lshlrev_b32_e32 v114, 16, v70
	v_and_b32_e32 v115, 0xffff0000, v70
	v_fma_f32 v108, -v188, v114, v112
	v_fma_f32 v109, -v188, v115, v113
	v_lshlrev_b32_e32 v112, 16, v67
	v_and_b32_e32 v113, 0xffff0000, v67
	v_lshlrev_b32_e32 v114, 16, v71
	v_and_b32_e32 v115, 0xffff0000, v71
	v_fma_f32 v110, -v188, v114, v112
	v_fma_f32 v111, -v188, v115, v113
	v_mul_f32_e32 v116, v104, v104
	v_mul_f32_e32 v117, v105, v105
	v_fmac_f32_e32 v116, v106, v106
	v_fmac_f32_e32 v117, v107, v107
	v_fmac_f32_e32 v116, v108, v108
	v_fmac_f32_e32 v117, v109, v109
	v_fmac_f32_e32 v116, v110, v110
	v_fmac_f32_e32 v117, v111, v111
	v_add_f32_e32 v116, v116, v117
	ds_bpermute_b32 v118, v207, v116
	s_waitcnt lgkmcnt(0)
	v_add_f32_e32 v116, v116, v118
	ds_bpermute_b32 v118, v208, v116
	s_waitcnt lgkmcnt(0)
	v_add_f32_e32 v116, v116, v118
	ds_bpermute_b32 v118, v209, v116
	s_waitcnt lgkmcnt(0)
	v_add_f32_e32 v116, v116, v118
	ds_bpermute_b32 v118, v210, v116
	s_waitcnt lgkmcnt(0)
	v_add_f32_e32 v116, v116, v118
	v_fmamk_f32 v116, v116, 0x3c000000, v193
	v_rsq_f32_e32 v120, v116
	s_nop 0
	v_mul_f32_e32 v120, v211, v120
	v_mul_f32_e32 v104, v104, v120
	v_mul_f32_e32 v105, v105, v120
	v_mul_f32_e32 v106, v106, v120
	v_mul_f32_e32 v107, v107, v120
	v_mul_f32_e32 v108, v108, v120
	v_mul_f32_e32 v109, v109, v120
	v_mul_f32_e32 v110, v110, v120
	v_mul_f32_e32 v111, v111, v120
	v_mul_f32_e32 v104, v4, v104
	v_mul_f32_e32 v105, v5, v105
	v_mul_f32_e32 v106, v6, v106
	v_mul_f32_e32 v107, v7, v107
	v_mul_f32_e32 v108, v0, v108
	v_mul_f32_e32 v109, v1, v109
	v_mul_f32_e32 v110, v2, v110
	v_mul_f32_e32 v111, v3, v111
	v_cvt_pk_bf16_f32 v124, v104, v105
	v_cvt_pk_bf16_f32 v125, v106, v107
	v_cvt_pk_bf16_f32 v126, v108, v109
	v_cvt_pk_bf16_f32 v127, v110, v111
	global_store_dwordx4 v[102:103], v[124:127], off
	v_lshl_add_u64 v[102:103], v[102:103], 0, s[98:99]
	s_waitcnt vmcnt(9)
	v_lshlrev_b32_e32 v112, 16, v72
	v_and_b32_e32 v113, 0xffff0000, v72
	v_lshlrev_b32_e32 v114, 16, v76
	v_and_b32_e32 v115, 0xffff0000, v76
	v_fma_f32 v104, -v188, v114, v112
	v_fma_f32 v105, -v188, v115, v113
	v_lshlrev_b32_e32 v112, 16, v73
	v_and_b32_e32 v113, 0xffff0000, v73
	v_lshlrev_b32_e32 v114, 16, v77
	v_and_b32_e32 v115, 0xffff0000, v77
	v_fma_f32 v106, -v188, v114, v112
	v_fma_f32 v107, -v188, v115, v113
	v_lshlrev_b32_e32 v112, 16, v74
	v_and_b32_e32 v113, 0xffff0000, v74
	v_lshlrev_b32_e32 v114, 16, v78
	v_and_b32_e32 v115, 0xffff0000, v78
	v_fma_f32 v108, -v188, v114, v112
	v_fma_f32 v109, -v188, v115, v113
	v_lshlrev_b32_e32 v112, 16, v75
	v_and_b32_e32 v113, 0xffff0000, v75
	v_lshlrev_b32_e32 v114, 16, v79
	v_and_b32_e32 v115, 0xffff0000, v79
	v_fma_f32 v110, -v188, v114, v112
	v_fma_f32 v111, -v188, v115, v113
	v_mul_f32_e32 v116, v104, v104
	v_mul_f32_e32 v117, v105, v105
	v_fmac_f32_e32 v116, v106, v106
	v_fmac_f32_e32 v117, v107, v107
	v_fmac_f32_e32 v116, v108, v108
	v_fmac_f32_e32 v117, v109, v109
	v_fmac_f32_e32 v116, v110, v110
	v_fmac_f32_e32 v117, v111, v111
	v_add_f32_e32 v116, v116, v117
	ds_bpermute_b32 v118, v207, v116
	s_waitcnt lgkmcnt(0)
	v_add_f32_e32 v116, v116, v118
	ds_bpermute_b32 v118, v208, v116
	s_waitcnt lgkmcnt(0)
	v_add_f32_e32 v116, v116, v118
	ds_bpermute_b32 v118, v209, v116
	s_waitcnt lgkmcnt(0)
	v_add_f32_e32 v116, v116, v118
	ds_bpermute_b32 v118, v210, v116
	s_waitcnt lgkmcnt(0)
	v_add_f32_e32 v116, v116, v118
	v_fmamk_f32 v116, v116, 0x3c000000, v193
	v_rsq_f32_e32 v120, v116
	s_nop 0
	v_mul_f32_e32 v120, v211, v120
	v_mul_f32_e32 v104, v104, v120
	v_mul_f32_e32 v105, v105, v120
	v_mul_f32_e32 v106, v106, v120
	v_mul_f32_e32 v107, v107, v120
	v_mul_f32_e32 v108, v108, v120
	v_mul_f32_e32 v109, v109, v120
	v_mul_f32_e32 v110, v110, v120
	v_mul_f32_e32 v111, v111, v120
	v_mul_f32_e32 v104, v4, v104
	v_mul_f32_e32 v105, v5, v105
	v_mul_f32_e32 v106, v6, v106
	v_mul_f32_e32 v107, v7, v107
	v_mul_f32_e32 v108, v0, v108
	v_mul_f32_e32 v109, v1, v109
	v_mul_f32_e32 v110, v2, v110
	v_mul_f32_e32 v111, v3, v111
	v_cvt_pk_bf16_f32 v124, v104, v105
	v_cvt_pk_bf16_f32 v125, v106, v107
	v_cvt_pk_bf16_f32 v126, v108, v109
	v_cvt_pk_bf16_f32 v127, v110, v111
	global_store_dwordx4 v[102:103], v[124:127], off
	v_lshl_add_u64 v[102:103], v[102:103], 0, s[98:99]
	s_waitcnt vmcnt(8)
; __device__ __forceinline__ float bf_lo(unsigned w) { return __uint_as_float(w << 16); }
; __device__ __forceinline__ float bf_hi(unsigned w) { return __uint_as_float(w & 0xffff0000u); }
; __device__ __forceinline__ float sumsq8(const f32x4 a, const f32x4 b) { return ((a[0] * a[0] + a[1] * a[1]) + (a[2] * a[2] + a[3] * a[3])) + ((b[0] * b[0] + b[1] * b[1]) + (b[2] * b[2] + b[3] * b[3])); }
; #define GAS __attribute__((address_space(1)))
; #define VM_WAIT() asm volatile("s_waitcnt vmcnt(0)" ::: "memory")
; __device__ __forceinline__ void attn_post(Frame& F, int l, int b, int h, int qb, float lam, float oscale) {
;     ...
;     for (int it = 0; it < 8; ++it) { const size_t row = rowbase + it * 4 + rsub;
;         const v4u a = __builtin_nontemporal_load((const GAS v4u*)(OV_ + row * D + h * 256 + e8)), c = __builtin_nontemporal_load((const GAS v4u*)(OV_ + row * D + h * 256 + 128 + e8));
;         f32x4 d0 = {pg8::bf_lo(a.x) - lam * pg8::bf_lo(c.x), pg8::bf_hi(a.x) - lam * pg8::bf_hi(c.x), pg8::bf_lo(a.y) - lam * pg8::bf_lo(c.y), pg8::bf_hi(a.y) - lam * pg8::bf_hi(c.y)};
;         f32x4 d1 = {pg8::bf_lo(a.z) - lam * pg8::bf_lo(c.z), pg8::bf_hi(a.z) - lam * pg8::bf_hi(c.z), pg8::bf_lo(a.w) - lam * pg8::bf_lo(c.w), pg8::bf_hi(a.w) - lam * pg8::bf_hi(c.w)};
;         float ss = pg8::sumsq8(d0, d1);
;         ss += __shfl_xor(ss, 1); ss += __shfl_xor(ss, 2); ss += __shfl_xor(ss, 4); ss += __shfl_xor(ss, 8);
;         const float rs = __builtin_amdgcn_rsqf(ss * (1.f / 128.f) + 1e-6f) * oscale;
;         d0 = d0 * rs * g0; d1 = d1 * rs * g1;
;         v4u o; o.x = pk2(d0.x, d0.y); o.y = pk2(d0.z, d0.w); o.z = pk2(d1.x, d1.y); o.w = pk2(d1.z, d1.w);
;         *(GAS v4u*)(AO_ + row * D + h * 128 + e8) = o; }
; __global__ void __launch_bounds__(NWAVES * 64, 2) hymba_fwd(Args args) {
;     ...
;                 for (int k = 0; k < 2; ++k) { const int qb = k ? 7 - s : s;
; #pragma unroll 1
;                     for (int c = 0; c < 2; ++c)
;                         attn2::attn_unit128<8>(qb, pj + (h * 2 + c) * 64, kimg + (size_t)((b * 8 + h * 2 + c) * 32) * 4096, vimg + (size_t)((b * 4 + h) * 32) * 8192, ov + h * 256 + c * 128, (char*)lds);
;                     VM_WAIT(); __syncthreads(); __builtin_amdgcn_fence(__ATOMIC_ACQUIRE, "agent"); VM_WAIT();
;                     attn_post(F, l, b, h, qb, lam, oscale);
	v_lshlrev_b32_e32 v112, 16, v80
	v_and_b32_e32 v113, 0xffff0000, v80
	v_lshlrev_b32_e32 v114, 16, v84
	v_and_b32_e32 v115, 0xffff0000, v84
	v_fma_f32 v104, -v188, v114, v112
	v_fma_f32 v105, -v188, v115, v113
	v_lshlrev_b32_e32 v112, 16, v81
	v_and_b32_e32 v113, 0xffff0000, v81
	v_lshlrev_b32_e32 v114, 16, v85
	v_and_b32_e32 v115, 0xffff0000, v85
	v_fma_f32 v106, -v188, v114, v112
	v_fma_f32 v107, -v188, v115, v113
	v_lshlrev_b32_e32 v112, 16, v82
	v_and_b32_e32 v113, 0xffff0000, v82
	v_lshlrev_b32_e32 v114, 16, v86
	v_and_b32_e32 v115, 0xffff0000, v86
	v_fma_f32 v108, -v188, v114, v112
	v_fma_f32 v109, -v188, v115, v113
	v_lshlrev_b32_e32 v112, 16, v83
	v_and_b32_e32 v113, 0xffff0000, v83
	v_lshlrev_b32_e32 v114, 16, v87
	v_and_b32_e32 v115, 0xffff0000, v87
	v_fma_f32 v110, -v188, v114, v112
	v_fma_f32 v111, -v188, v115, v113
	v_mul_f32_e32 v116, v104, v104
	v_mul_f32_e32 v117, v105, v105
	v_fmac_f32_e32 v116, v106, v106
	v_fmac_f32_e32 v117, v107, v107
	v_fmac_f32_e32 v116, v108, v108
	v_fmac_f32_e32 v117, v109, v109
	v_fmac_f32_e32 v116, v110, v110
	v_fmac_f32_e32 v117, v111, v111
	v_add_f32_e32 v116, v116, v117
	ds_bpermute_b32 v118, v207, v116
	s_waitcnt lgkmcnt(0)
	v_add_f32_e32 v116, v116, v118
	ds_bpermute_b32 v118, v208, v116
	s_waitcnt lgkmcnt(0)
	v_add_f32_e32 v116, v116, v118
	ds_bpermute_b32 v118, v209, v116
	s_waitcnt lgkmcnt(0)
	v_add_f32_e32 v116, v116, v118
	ds_bpermute_b32 v118, v210, v116
	s_waitcnt lgkmcnt(0)
	v_add_f32_e32 v116, v116, v118
	v_fmamk_f32 v116, v116, 0x3c000000, v193
	v_rsq_f32_e32 v120, v116
	s_nop 0
	v_mul_f32_e32 v120, v211, v120
	v_mul_f32_e32 v104, v104, v120
	v_mul_f32_e32 v105, v105, v120
	v_mul_f32_e32 v106, v106, v120
	v_mul_f32_e32 v107, v107, v120
	v_mul_f32_e32 v108, v108, v120
	v_mul_f32_e32 v109, v109, v120
	v_mul_f32_e32 v110, v110, v120
	v_mul_f32_e32 v111, v111, v120
	v_mul_f32_e32 v104, v4, v104
	v_mul_f32_e32 v105, v5, v105
	v_mul_f32_e32 v106, v6, v106
	v_mul_f32_e32 v107, v7, v107
	v_mul_f32_e32 v108, v0, v108
	v_mul_f32_e32 v109, v1, v109
	v_mul_f32_e32 v110, v2, v110
	v_mul_f32_e32 v111, v3, v111
	v_cvt_pk_bf16_f32 v124, v104, v105
	v_cvt_pk_bf16_f32 v125, v106, v107
	v_cvt_pk_bf16_f32 v126, v108, v109
	v_cvt_pk_bf16_f32 v127, v110, v111
	global_store_dwordx4 v[102:103], v[124:127], off
	v_lshl_add_u64 v[102:103], v[102:103], 0, s[98:99]
	s_waitcnt vmcnt(7)
	v_lshlrev_b32_e32 v112, 16, v88
	v_and_b32_e32 v113, 0xffff0000, v88
	v_lshlrev_b32_e32 v114, 16, v92
	v_and_b32_e32 v115, 0xffff0000, v92
	v_fma_f32 v104, -v188, v114, v112
	v_fma_f32 v105, -v188, v115, v113
	v_lshlrev_b32_e32 v112, 16, v89
	v_and_b32_e32 v113, 0xffff0000, v89
	v_lshlrev_b32_e32 v114, 16, v93
	v_and_b32_e32 v115, 0xffff0000, v93
	v_fma_f32 v106, -v188, v114, v112
	v_fma_f32 v107, -v188, v115, v113
	v_lshlrev_b32_e32 v112, 16, v90
	v_and_b32_e32 v113, 0xffff0000, v90
	v_lshlrev_b32_e32 v114, 16, v94
	v_and_b32_e32 v115, 0xffff0000, v94
	v_fma_f32 v108, -v188, v114, v112
	v_fma_f32 v109, -v188, v115, v113
	v_lshlrev_b32_e32 v112, 16, v91
	v_and_b32_e32 v113, 0xffff0000, v91
	v_lshlrev_b32_e32 v114, 16, v95
	v_and_b32_e32 v115, 0xffff0000, v95
	v_fma_f32 v110, -v188, v114, v112
	v_fma_f32 v111, -v188, v115, v113
	v_mul_f32_e32 v116, v104, v104
	v_mul_f32_e32 v117, v105, v105
	v_fmac_f32_e32 v116, v106, v106
	v_fmac_f32_e32 v117, v107, v107
	v_fmac_f32_e32 v116, v108, v108
	v_fmac_f32_e32 v117, v109, v109
	v_fmac_f32_e32 v116, v110, v110
	v_fmac_f32_e32 v117, v111, v111
	v_add_f32_e32 v116, v116, v117
	ds_bpermute_b32 v118, v207, v116
	s_waitcnt lgkmcnt(0)
	v_add_f32_e32 v116, v116, v118
	ds_bpermute_b32 v118, v208, v116
	s_waitcnt lgkmcnt(0)
	v_add_f32_e32 v116, v116, v118
	ds_bpermute_b32 v118, v209, v116
	s_waitcnt lgkmcnt(0)
	v_add_f32_e32 v116, v116, v118
	ds_bpermute_b32 v118, v210, v116
	s_waitcnt lgkmcnt(0)
	v_add_f32_e32 v116, v116, v118
	v_fmamk_f32 v116, v116, 0x3c000000, v193
	v_rsq_f32_e32 v120, v116
	s_nop 0
	v_mul_f32_e32 v120, v211, v120
	v_mul_f32_e32 v104, v104, v120
	v_mul_f32_e32 v105, v105, v120
	v_mul_f32_e32 v106, v106, v120
	v_mul_f32_e32 v107, v107, v120
	v_mul_f32_e32 v108, v108, v120
	v_mul_f32_e32 v109, v109, v120
	v_mul_f32_e32 v110, v110, v120
	v_mul_f32_e32 v111, v111, v120
	v_mul_f32_e32 v104, v4, v104
	v_mul_f32_e32 v105, v5, v105
	v_mul_f32_e32 v106, v6, v106
	v_mul_f32_e32 v107, v7, v107
	v_mul_f32_e32 v108, v0, v108
	v_mul_f32_e32 v109, v1, v109
	v_mul_f32_e32 v110, v2, v110
	v_mul_f32_e32 v111, v3, v111
	v_cvt_pk_bf16_f32 v124, v104, v105
	v_cvt_pk_bf16_f32 v125, v106, v107
	v_cvt_pk_bf16_f32 v126, v108, v109
	v_cvt_pk_bf16_f32 v127, v110, v111
	global_store_dwordx4 v[102:103], v[124:127], off
	s_mov_b64 s[0:1], 0
	s_cbranch_vccnz .LBB0_360
